# attention softmax: MFMA->max pad 24 -> 12 wait states (ISA minimum for an 8-pass MFMA) and removed the s_nop 0 the compiler put after each inline-asm v_max3 (no hardware hazard VALU->VALU)
# baseline (speedup 1.0000x reference)
; #define LAS __attribute__((address_space(3)))
; template <int MODE, bool WINDOW>
; __device__ __forceinline__ void attn_tile(const LAS unsigned char* buf, const bf16x8* qr, f32x16* o, float& m, float& l, int qpos, int kbase, int r32, int hi, const bool CAUSAL) {
;     ...
;     asm volatile("s_nop 15\n\ts_nop 7" : "+v"(p0), "+v"(p1));
;     float mxa = max3f(p0[0], p1[0], p0[1]), mxb = max3f(p1[1], p0[2], p1[2]);
; #pragma unroll
;     for (int r = 3; r < 15; r += 2) { mxa = max3f(mxa, p0[r], p1[r]); mxb = max3f(mxb, p0[r + 1], p1[r + 1]); }
;     mxa = max3f(mxa, p0[15], p1[15]);
;     const float mx = xhalf_max(max2f(mxa, mxb));
;     bf16x8 va[4], vb[4];
; #pragma unroll
;     for (int g = 0; g < 4; ++g) {
;         const LAS unsigned char* vp = Vt + (32 * (g & 1) + r32) * VT_PITCH + (16 * (g >> 1) + 4 * hi) * 2;
;         const s16x4 lo = *(const LAS s16x4*)vp, h4 = *(const LAS s16x4*)(vp + 16), lo2 = *(const LAS s16x4*)(vp + 64), h42 = *(const LAS s16x4*)(vp + 80);
;         va[g] = (bf16x8){lo[0], lo[1], lo[2], lo[3], h4[0], h4[1], h4[2], h4[3]};
;         vb[g] = (bf16x8){lo2[0], lo2[1], lo2[2], lo2[3], h42[0], h42[1], h42[2], h42[3]};
;     }
;     const float mn = max2f(m, mx);
;     if (__any(mn > m)) {
;         const float alpha = __builtin_amdgcn_exp2f((m - mn) * LOG2E);
;         l *= alpha;
; #pragma unroll
;         for (int r = 0; r < 16; ++r) { o[0][r] *= alpha; o[1][r] *= alpha; }
;     }
;     m = mn;
;     const float nm2 = -mn * LOG2E;
;     float rs = 0.f;
; #pragma unroll
;     for (int r = 0; r < 16; ++r) { p0[r] = __builtin_amdgcn_exp2f(__builtin_fmaf(p0[r], LOG2E, nm2)); rs += p0[r]; }
;     v4u pw0, pw1;
;     pw0.x = cvtpk(p0[0], p0[1]); pw0.y = cvtpk(p0[2], p0[3]); pw0.z = cvtpk(p0[4], p0[5]); pw0.w = cvtpk(p0[6], p0[7]);
;     pw1.x = cvtpk(p0[8], p0[9]); pw1.y = cvtpk(p0[10], p0[11]); pw1.z = cvtpk(p0[12], p0[13]); pw1.w = cvtpk(p0[14], p0[15]);
;     __builtin_amdgcn_sched_barrier(0);
; #pragma unroll
;     for (int g = 0; g < 4; ++g) {
;         o[g & 1] = __builtin_amdgcn_mfma_f32_32x32x16_bf16(va[g], __builtin_bit_cast(bf16x8, (g >> 1) ? pw1 : pw0), o[g & 1], 0, 0, 0);
; #pragma unroll
;         for (int e = 0; e < 4; ++e) { p1[4 * g + e] = __builtin_amdgcn_exp2f(__builtin_fmaf(p1[4 * g + e], LOG2E, nm2)); rs += p1[4 * g + e]; }
;         __builtin_amdgcn_sched_barrier(0);
;     }
;     l += rs;
.LBB0_209:
	s_nop 11
	s_mov_b32 s22, 0xff800000
	v_max3_f32 v0, v2, v30, v3
	v_max3_f32 v18, v31, v4, v32
	v_add_u32_e32 v22, 0x6800, v166
	v_max3_f32 v0, v0, v5, v33
	v_max3_f32 v18, v18, v6, v34
	v_add_u32_e32 v23, 0x7800, v166
	v_max3_f32 v0, v0, v7, v35
	v_max3_f32 v18, v18, v8, v36
	ds_read2_b64 v[94:97], v22 offset0:136 offset1:138
	v_max3_f32 v0, v0, v9, v37
	v_max3_f32 v18, v18, v10, v38
	v_max3_f32 v0, v0, v11, v39
	v_max3_f32 v18, v18, v12, v40
	v_max3_f32 v0, v0, v13, v41
	v_max3_f32 v18, v18, v14, v42
	v_max3_f32 v0, v0, v15, v43
	v_max3_f32 v18, v18, v16, v44
	v_max3_f32 v0, v0, v17, v45
	v_max_f32_e32 v0, v0, v18
	v_mov_b32_e32 v18, v0
	s_nop 1
	v_permlane32_swap_b32_e32 v0, v18
	v_max_f32_e32 v0, v0, v18
	ds_read2_b64 v[104:107], v23 offset0:160 offset1:162
	ds_read2_b64 v[98:101], v23 offset0:168 offset1:170
	ds_read2_b64 v[18:21], v22 offset0:128 offset1:130
	ds_read2_b64 v[108:111], v22 offset0:132 offset1:134
	ds_read2_b64 v[62:65], v22 offset0:140 offset1:142
	v_max_f32_e32 v172, v191, v0
	ds_read2_b64 v[112:115], v23 offset0:164 offset1:166
	ds_read2_b64 v[90:93], v23 offset0:172 offset1:174
	v_sub_f32_e32 v0, 0xff800000, v172
	v_mul_f32_e32 v0, 0x3fb8aa3b, v0
	v_exp_f32_e32 v0, v0
	v_cmp_neq_f32_e32 vcc, s22, v172
	s_cmp_lg_u64 vcc, 0
	s_cselect_b64 vcc, -1, 0
	v_mul_f32_e32 v0, 0, v0
	v_cndmask_b32_e32 v46, 0, v0, vcc
	v_mul_f32_e32 v0, 0xbfb8aa3b, v172
	v_fmamk_f32 v2, v2, 0x3fb8aa3b, v0
	v_exp_f32_e32 v2, v2
	v_fmamk_f32 v3, v3, 0x3fb8aa3b, v0
	v_exp_f32_e32 v3, v3
	v_fmamk_f32 v4, v4, 0x3fb8aa3b, v0
	v_exp_f32_e32 v4, v4
	v_fmamk_f32 v5, v5, 0x3fb8aa3b, v0
	v_exp_f32_e32 v5, v5
	v_fmamk_f32 v6, v6, 0x3fb8aa3b, v0
	v_add_f32_e32 v22, 0, v2
	v_exp_f32_e32 v6, v6
	v_fmamk_f32 v7, v7, 0x3fb8aa3b, v0
	v_add_f32_e32 v22, v3, v22
	v_exp_f32_e32 v7, v7
	v_fmamk_f32 v8, v8, 0x3fb8aa3b, v0
	v_add_f32_e32 v22, v4, v22
	v_exp_f32_e32 v8, v8
	v_fmamk_f32 v9, v9, 0x3fb8aa3b, v0
	v_add_f32_e32 v22, v5, v22
	v_exp_f32_e32 v9, v9
	v_fmamk_f32 v10, v10, 0x3fb8aa3b, v0
	v_add_f32_e32 v22, v6, v22
	v_exp_f32_e32 v10, v10
	v_fmamk_f32 v11, v11, 0x3fb8aa3b, v0
	v_add_f32_e32 v22, v7, v22
	v_exp_f32_e32 v11, v11
	v_fmamk_f32 v12, v12, 0x3fb8aa3b, v0
	v_add_f32_e32 v22, v8, v22
	v_exp_f32_e32 v12, v12
	v_fmamk_f32 v13, v13, 0x3fb8aa3b, v0
	v_add_f32_e32 v22, v9, v22
	v_exp_f32_e32 v13, v13
	v_fmamk_f32 v14, v14, 0x3fb8aa3b, v0
	v_add_f32_e32 v22, v10, v22
	v_exp_f32_e32 v14, v14
	v_fmamk_f32 v15, v15, 0x3fb8aa3b, v0
	v_add_f32_e32 v22, v11, v22
	v_exp_f32_e32 v15, v15
	v_fmamk_f32 v16, v16, 0x3fb8aa3b, v0
	v_add_f32_e32 v22, v12, v22
	v_exp_f32_e32 v16, v16
	v_fmamk_f32 v17, v17, 0x3fb8aa3b, v0
	v_add_f32_e32 v22, v13, v22
	v_exp_f32_e32 v17, v17
	v_add_f32_e32 v22, v14, v22
	v_add_f32_e32 v22, v15, v22
	v_add_f32_e32 v22, v16, v22
	v_add_f32_e32 v22, v17, v22
	v_cvt_pk_bf16_f32 v116, v2, v3
	v_cvt_pk_bf16_f32 v117, v4, v5
	v_cvt_pk_bf16_f32 v118, v6, v7
	v_cvt_pk_bf16_f32 v119, v8, v9
	v_cvt_pk_bf16_f32 v174, v10, v11
	v_cvt_pk_bf16_f32 v175, v12, v13
	v_cvt_pk_bf16_f32 v176, v14, v15
	v_cvt_pk_bf16_f32 v177, v16, v17
	v_mov_b32_e32 v47, v46
	v_mov_b32_e32 v48, v46
	v_mov_b32_e32 v49, v46
	v_mov_b32_e32 v50, v46
	v_mov_b32_e32 v51, v46
	v_mov_b32_e32 v52, v46
	v_mov_b32_e32 v53, v46
	v_mov_b32_e32 v54, v46
	v_mov_b32_e32 v55, v46
	v_mov_b32_e32 v56, v46
	v_mov_b32_e32 v57, v46
	v_mov_b32_e32 v58, v46
	v_mov_b32_e32 v59, v46
	v_mov_b32_e32 v60, v46
	v_mov_b32_e32 v61, v46
	s_waitcnt lgkmcnt(4)
	s_nop 0
	v_mfma_f32_32x32x16_bf16 v[2:17], v[18:21], v[116:119], v[46:61]
	v_fmamk_f32 v18, v30, 0x3fb8aa3b, v0
	v_exp_f32_e32 v103, v18
	v_fmamk_f32 v18, v31, 0x3fb8aa3b, v0
	v_exp_f32_e32 v120, v18
	v_fmamk_f32 v18, v32, 0x3fb8aa3b, v0
	v_exp_f32_e32 v121, v18
	v_fmamk_f32 v18, v33, 0x3fb8aa3b, v0
	v_exp_f32_e32 v173, v18
	v_add_f32_e32 v18, v103, v22
	v_add_f32_e32 v18, v120, v18
	v_add_f32_e32 v18, v121, v18
	v_add_f32_e32 v171, v173, v18
	v_mov_b64_e32 v[18:19], v[46:47]
	v_mov_b64_e32 v[20:21], v[48:49]
	v_mov_b64_e32 v[22:23], v[50:51]
	v_mov_b64_e32 v[24:25], v[52:53]
	v_mov_b64_e32 v[26:27], v[54:55]
	v_mov_b64_e32 v[28:29], v[56:57]
	v_mov_b64_e32 v[30:31], v[58:59]
	v_mov_b64_e32 v[32:33], v[60:61]
	v_fmamk_f32 v34, v34, 0x3fb8aa3b, v0
	v_exp_f32_e32 v47, v34
	v_mfma_f32_32x32x16_bf16 v[18:33], v[104:107], v[116:119], v[18:33]
	v_fmamk_f32 v34, v35, 0x3fb8aa3b, v0
	v_exp_f32_e32 v48, v34
	v_fmamk_f32 v34, v36, 0x3fb8aa3b, v0
	v_exp_f32_e32 v49, v34
	v_fmamk_f32 v34, v37, 0x3fb8aa3b, v0
	v_exp_f32_e32 v37, v34
	v_add_f32_e32 v34, v47, v171
	v_add_f32_e32 v34, v48, v34
	v_add_f32_e32 v34, v49, v34
	v_add_f32_e32 v34, v37, v34
	s_waitcnt lgkmcnt(3)
	v_mfma_f32_32x32x16_bf16 v[2:17], v[108:111], v[174:177], v[2:17]
	v_fmamk_f32 v35, v38, 0x3fb8aa3b, v0
	v_exp_f32_e32 v38, v35
	v_fmamk_f32 v35, v39, 0x3fb8aa3b, v0
	v_exp_f32_e32 v39, v35
	v_fmamk_f32 v35, v40, 0x3fb8aa3b, v0
	v_exp_f32_e32 v40, v35
	v_fmamk_f32 v35, v41, 0x3fb8aa3b, v0
	v_exp_f32_e32 v41, v35
	v_add_f32_e32 v34, v38, v34
	v_add_f32_e32 v34, v39, v34
	v_add_f32_e32 v34, v40, v34
	v_add_f32_e32 v34, v41, v34
	s_waitcnt lgkmcnt(1)
	v_mfma_f32_32x32x16_bf16 v[18:33], v[112:115], v[174:177], v[18:33]
	v_fmamk_f32 v35, v42, 0x3fb8aa3b, v0
	v_exp_f32_e32 v42, v35
	v_fmamk_f32 v35, v43, 0x3fb8aa3b, v0
	v_exp_f32_e32 v43, v35
	v_fmamk_f32 v35, v44, 0x3fb8aa3b, v0
	v_exp_f32_e32 v44, v35
	v_fmac_f32_e32 v0, 0x3fb8aa3b, v45
	v_exp_f32_e32 v0, v0
	v_add_f32_e32 v34, v42, v34
	v_add_f32_e32 v34, v43, v34
	v_add_f32_e32 v34, v44, v34
	v_add_f32_e32 v34, v0, v34
	v_add_f32_e32 v171, v46, v34
	v_cvt_pk_bf16_f32 v34, v103, v120
	v_cvt_pk_bf16_f32 v35, v121, v173
	v_cvt_pk_bf16_f32 v36, v47, v48
	v_cvt_pk_bf16_f32 v37, v49, v37
	v_cvt_pk_bf16_f32 v38, v38, v39
	v_cvt_pk_bf16_f32 v39, v40, v41
	v_mfma_f32_32x32x16_bf16 v[2:17], v[94:97], v[34:37], v[2:17]
	v_cvt_pk_bf16_f32 v40, v42, v43
	v_cvt_pk_bf16_f32 v41, v44, v0
	v_mfma_f32_32x32x16_bf16 v[18:33], v[98:101], v[34:37], v[18:33]
	s_nop 0
	v_mfma_f32_32x32x16_bf16 v[2:17], v[62:65], v[38:41], v[2:17]
	s_waitcnt lgkmcnt(0)
	v_mfma_f32_32x32x16_bf16 v[18:33], v[90:93], v[38:41], v[18:33]
	s_branch .LBB0_217

; #define LAS __attribute__((address_space(3)))
; __device__ __forceinline__ float max3f(float a, float b, float c) { float r; asm("v_max3_f32 %0, %1, %2, %3" : "=v"(r) : "v"(a), "v"(b), "v"(c)); return r; }
; __device__ __forceinline__ float max2f(float a, float b) { float r; asm("v_max_f32_e32 %0, %1, %2" : "=v"(r) : "v"(a), "v"(b)); return r; }
; __device__ __forceinline__ float xhalf_max(float v) { auto rr = __builtin_amdgcn_permlane32_swap(__float_as_uint(v), __float_as_uint(v), false, false); return max2f(__uint_as_float(rr[0]), __uint_as_float(rr[1])); }
; template <int MODE, bool WINDOW>
; __device__ __forceinline__ void attn_tile(const LAS unsigned char* buf, const bf16x8* qr, f32x16* o, float& m, float& l, int qpos, int kbase, int r32, int hi, const bool CAUSAL) {
;     ...
;     asm volatile("s_nop 15\n\ts_nop 7" : "+v"(p0), "+v"(p1));
;     float mxa = max3f(p0[0], p1[0], p0[1]), mxb = max3f(p1[1], p0[2], p1[2]);
; #pragma unroll
;     for (int r = 3; r < 15; r += 2) { mxa = max3f(mxa, p0[r], p1[r]); mxb = max3f(mxb, p0[r + 1], p1[r + 1]); }
;     mxa = max3f(mxa, p0[15], p1[15]);
;     const float mx = xhalf_max(max2f(mxa, mxb));
;     bf16x8 va[4], vb[4];
; #pragma unroll
;     for (int g = 0; g < 4; ++g) {
;         const LAS unsigned char* vp = Vt + (32 * (g & 1) + r32) * VT_PITCH + (16 * (g >> 1) + 4 * hi) * 2;
;         const s16x4 lo = *(const LAS s16x4*)vp, h4 = *(const LAS s16x4*)(vp + 16), lo2 = *(const LAS s16x4*)(vp + 64), h42 = *(const LAS s16x4*)(vp + 80);
;         va[g] = (bf16x8){lo[0], lo[1], lo[2], lo[3], h4[0], h4[1], h4[2], h4[3]};
;         vb[g] = (bf16x8){lo2[0], lo2[1], lo2[2], lo2[3], h42[0], h42[1], h42[2], h42[3]};
;     }
;     const float mn = max2f(m, mx);
;     if (__any(mn > m)) {
;         const float alpha = __builtin_amdgcn_exp2f((m - mn) * LOG2E);
;         l *= alpha;
; #pragma unroll
;         for (int r = 0; r < 16; ++r) { o[0][r] *= alpha; o[1][r] *= alpha; }
;     }
.LBB0_241:
	s_nop 11
	s_nop 0
	v_max3_f32 v90, v50, v34, v51
	v_max3_f32 v91, v35, v52, v36
	v_max3_f32 v90, v90, v53, v37
	v_max3_f32 v91, v91, v54, v38
	v_max3_f32 v90, v90, v55, v39
	v_max3_f32 v91, v91, v56, v40
	v_max3_f32 v90, v90, v57, v41
	v_max3_f32 v91, v91, v58, v42
	v_max3_f32 v90, v90, v59, v43
	v_max3_f32 v91, v91, v60, v44
	v_max3_f32 v90, v90, v61, v45
	v_max3_f32 v91, v91, v62, v46
	v_max3_f32 v90, v90, v63, v47
	v_max3_f32 v91, v91, v64, v48
	v_max3_f32 v90, v90, v65, v49
	v_max_f32_e32 v90, v90, v91
	v_mov_b32_e32 v91, v90
	s_nop 1
	v_permlane32_swap_b32_e32 v90, v91
	v_max_f32_e32 v173, v90, v91
	v_add3_u32 v90, s22, v163, v126
	v_add_u32_e32 v91, 0x2000, v90
	v_add_u32_e32 v90, 0x3000, v90
	ds_read2_b64 v[118:121], v91 offset0:128 offset1:130
	ds_read2_b64 v[110:113], v91 offset0:132 offset1:134
	ds_read2_b64 v[98:101], v91 offset0:136 offset1:138
	ds_read2_b64 v[114:117], v90 offset0:160 offset1:162
	s_waitcnt vmcnt(6)
	ds_read2_b64 v[102:105], v90 offset0:168 offset1:170
	ds_read2_b64 v[94:97], v91 offset0:140 offset1:142
	ds_read2_b64 v[106:109], v90 offset0:164 offset1:166
	ds_read2_b64 v[90:93], v90 offset0:172 offset1:174
	v_max_f32_e32 v173, v172, v173
	s_nop 0
	v_cmp_gt_f32_e32 vcc, v173, v172
	s_cbranch_vccz .LBB0_243
	v_sub_f32_e32 v172, v172, v173
	v_mul_f32_e32 v172, 0x3fb8aa3b, v172
	v_exp_f32_e32 v172, v172
	s_nop 0
	v_mul_f32_e32 v171, v171, v172
	v_pk_mul_f32 v[32:33], v[32:33], v[172:173] op_sel_hi:[1,0]
	v_pk_mul_f32 v[30:31], v[30:31], v[172:173] op_sel_hi:[1,0]
	v_pk_mul_f32 v[28:29], v[28:29], v[172:173] op_sel_hi:[1,0]
	v_pk_mul_f32 v[26:27], v[26:27], v[172:173] op_sel_hi:[1,0]
	v_pk_mul_f32 v[24:25], v[24:25], v[172:173] op_sel_hi:[1,0]
	v_pk_mul_f32 v[22:23], v[22:23], v[172:173] op_sel_hi:[1,0]
	v_pk_mul_f32 v[20:21], v[20:21], v[172:173] op_sel_hi:[1,0]
	v_pk_mul_f32 v[18:19], v[18:19], v[172:173] op_sel_hi:[1,0]
	v_pk_mul_f32 v[16:17], v[16:17], v[172:173] op_sel_hi:[1,0]
	v_pk_mul_f32 v[14:15], v[14:15], v[172:173] op_sel_hi:[1,0]
	v_pk_mul_f32 v[12:13], v[12:13], v[172:173] op_sel_hi:[1,0]
	v_pk_mul_f32 v[10:11], v[10:11], v[172:173] op_sel_hi:[1,0]
	v_pk_mul_f32 v[8:9], v[8:9], v[172:173] op_sel_hi:[1,0]
	v_pk_mul_f32 v[6:7], v[6:7], v[172:173] op_sel_hi:[1,0]
	v_pk_mul_f32 v[4:5], v[4:5], v[172:173] op_sel_hi:[1,0]
	v_pk_mul_f32 v[2:3], v[2:3], v[172:173] op_sel_hi:[1,0]

; #define LAS __attribute__((address_space(3)))
; __device__ __forceinline__ unsigned cvtpk(float lo, float hi) { f32x2_t v = {lo, hi}; bf16x2_t b = __builtin_convertvector(v, bf16x2_t); return __builtin_bit_cast(unsigned, b); }
; __device__ __forceinline__ bf16x8 scale_q(v4u w) {
;     const unsigned ww[4] = {w.x, w.y, w.z, w.w}; unsigned r[4];
; #pragma unroll
;     for (int i = 0; i < 4; ++i) r[i] = cvtpk(bf2f((unsigned short)(ww[i] & 0xffffu)) * 0.125f, bf2f((unsigned short)(ww[i] >> 16)) * 0.125f);
;     v4u o; o.x = r[0]; o.y = r[1]; o.z = r[2]; o.w = r[3]; return __builtin_bit_cast(bf16x8, o);
; template <int MODE, bool WINDOW>
; __device__ __forceinline__ void attn_tile(const LAS unsigned char* buf, const bf16x8* qr, f32x16* o, float& m, float& l, int qpos, int kbase, int r32, int hi, const bool CAUSAL) {
;     ...
; #pragma unroll
;     for (int d0 = 0; d0 < 4; ++d0) {
;         const bf16x8 a0 = *(const LAS bf16x8*)(Ks + r32 * KS_PITCH + d0 * 32 + hi * 16);
;         const bf16x8 a1 = *(const LAS bf16x8*)(Ks + (32 + r32) * KS_PITCH + d0 * 32 + hi * 16);
;         p0 = __builtin_amdgcn_mfma_f32_32x32x16_bf16(a0, qr[d0], p0, 0, 0, 0);
;         p1 = __builtin_amdgcn_mfma_f32_32x32x16_bf16(a1, qr[d0], p1, 0, 0, 0);
;     }
;     if (CAUSAL || WINDOW) {
; #pragma unroll
;         for (int r = 0; r < 16; ++r) {
;             const int kv0 = kbase + (r & 3) + 8 * (r >> 2) + 4 * hi, kv1 = kv0 + 32;
;             bool v0 = true, v1 = true;
;             if (CAUSAL) { v0 = kv0 <= qpos; v1 = kv1 <= qpos; }
;             if (WINDOW) { v0 = v0 && (qpos - kv0 < 128); v1 = v1 && (qpos - kv1 < 128); }
;             p0[r] = v0 ? p0[r] : -INFINITY; p1[r] = v1 ? p1[r] : -INFINITY;
;         }
;     }
.LBB0_273:
	v_lshlrev_b32_e32 v6, 16, v2
	v_and_b32_e32 v7, 0xffff0000, v2
	v_lshlrev_b32_e32 v2, 16, v3
	v_and_b32_e32 v3, 0xffff0000, v3
	v_pk_mul_f32 v[2:3], v[2:3], s[90:91] op_sel_hi:[1,0]
	v_add3_u32 v0, s29, v179, v199
	v_cvt_pk_bf16_f32 v93, v2, v3
	v_lshlrev_b32_e32 v2, 16, v4
	v_and_b32_e32 v3, 0xffff0000, v4
	v_pk_mul_f32 v[2:3], v[2:3], s[90:91] op_sel_hi:[1,0]
	v_pk_mul_f32 v[6:7], v[6:7], s[90:91] op_sel_hi:[1,0]
	v_cvt_pk_bf16_f32 v94, v2, v3
	v_lshlrev_b32_e32 v2, 16, v5
	v_and_b32_e32 v3, 0xffff0000, v5
	v_pk_mul_f32 v[2:3], v[2:3], s[90:91] op_sel_hi:[1,0]
	v_cvt_pk_bf16_f32 v92, v6, v7
	v_cvt_pk_bf16_f32 v95, v2, v3
	v_lshlrev_b32_e32 v2, 16, v28
	v_and_b32_e32 v3, 0xffff0000, v28
	v_pk_mul_f32 v[2:3], v[2:3], s[90:91] op_sel_hi:[1,0]
	v_lshlrev_b32_e32 v6, 16, v29
	v_cvt_pk_bf16_f32 v96, v2, v3
	ds_read_b128 v[2:5], v0
	v_and_b32_e32 v7, 0xffff0000, v29
	v_pk_mul_f32 v[6:7], v[6:7], s[90:91] op_sel_hi:[1,0]
	ds_read_b128 v[32:35], v0 offset:4608
	ds_read_b128 v[50:53], v0 offset:32
	v_cvt_pk_bf16_f32 v97, v6, v7
	v_lshlrev_b32_e32 v6, 16, v30
	v_and_b32_e32 v7, 0xffff0000, v30
	v_pk_mul_f32 v[28:29], v[6:7], s[90:91] op_sel_hi:[1,0]
	s_waitcnt lgkmcnt(2)
	v_mfma_f32_32x32x16_bf16 v[4:19], v[2:5], v[92:95], 0
	v_lshlrev_b32_e32 v2, 16, v31
	v_and_b32_e32 v3, 0xffff0000, v31
	v_cvt_pk_bf16_f32 v98, v28, v29
	v_mul_f32_e64 v2, v2, s90
	v_mul_f32_e64 v3, v3, s90
	ds_read_b128 v[28:31], v0 offset:4640
	v_cvt_pk_bf16_f32 v99, v2, v3
	v_lshlrev_b32_e32 v2, 16, v24
	s_waitcnt lgkmcnt(2)
	v_mfma_f32_32x32x16_bf16 v[34:49], v[32:35], v[92:95], 0
	v_and_b32_e32 v3, 0xffff0000, v24
	v_mul_f32_e64 v2, v2, s90
	v_mul_f32_e64 v3, v3, s90
	v_add_u32_e32 v204, s18, v200
	v_cvt_pk_bf16_f32 v100, v2, v3
	v_lshlrev_b32_e32 v2, 16, v25
	v_and_b32_e32 v3, 0xffff0000, v25
	v_pk_mul_f32 v[2:3], v[2:3], s[90:91] op_sel_hi:[1,0]
	s_waitcnt lgkmcnt(1)
	v_mfma_f32_32x32x16_bf16 v[4:19], v[50:53], v[96:99], v[4:19]
	v_cvt_pk_bf16_f32 v101, v2, v3
	v_lshlrev_b32_e32 v2, 16, v26
	v_and_b32_e32 v3, 0xffff0000, v26
	v_mul_f32_e64 v2, v2, s90
	v_mul_f32_e64 v3, v3, s90
	v_cvt_pk_bf16_f32 v102, v2, v3
	v_lshlrev_b32_e32 v2, 16, v27
	v_and_b32_e32 v3, 0xffff0000, v27
	ds_read_b128 v[24:27], v0 offset:64
	s_waitcnt lgkmcnt(1)
	v_mfma_f32_32x32x16_bf16 v[34:49], v[28:31], v[96:99], v[34:49]
	ds_read_b128 v[28:31], v0 offset:4672
	ds_read_b128 v[50:53], v0 offset:96
	v_mul_f32_e64 v2, v2, s90
	v_mul_f32_e64 v3, v3, s90
	v_cvt_pk_bf16_f32 v103, v2, v3
	v_lshlrev_b32_e32 v2, 16, v20
	v_and_b32_e32 v3, 0xffff0000, v20
	v_pk_mul_f32 v[2:3], v[2:3], s[90:91] op_sel_hi:[1,0]
	s_waitcnt lgkmcnt(2)
	v_mfma_f32_32x32x16_bf16 v[4:19], v[24:27], v[100:103], v[4:19]
	ds_read_b128 v[24:27], v0 offset:4704
	v_cvt_pk_bf16_f32 v104, v2, v3
	v_lshlrev_b32_e32 v2, 16, v21
	v_and_b32_e32 v3, 0xffff0000, v21
	v_mul_f32_e64 v2, v2, s90
	v_mul_f32_e64 v3, v3, s90
	v_add_u32_e32 v0, s18, v144
	v_cvt_pk_bf16_f32 v105, v2, v3
	s_waitcnt lgkmcnt(2)
	v_mfma_f32_32x32x16_bf16 v[34:49], v[28:31], v[100:103], v[34:49]
	v_lshlrev_b32_e32 v2, 16, v22
	v_and_b32_e32 v3, 0xffff0000, v22
	v_mul_f32_e64 v2, v2, s90
	v_mul_f32_e64 v3, v3, s90
	v_cvt_pk_bf16_f32 v106, v2, v3
	v_lshlrev_b32_e32 v2, 16, v23
	v_and_b32_e32 v3, 0xffff0000, v23
	v_pk_mul_f32 v[2:3], v[2:3], s[90:91] op_sel_hi:[1,0]
	s_nop 0
	v_cvt_pk_bf16_f32 v107, v2, v3
	v_add_u32_e32 v2, 32, v204
	v_cmp_le_u32_e32 vcc, v2, v0
	s_waitcnt lgkmcnt(0)
	v_mfma_f32_32x32x16_bf16 v[34:49], v[24:27], v[104:107], v[34:49]
	v_add_u32_e32 v2, 33, v204
	v_add_u32_e32 v3, 34, v204
	v_mfma_f32_32x32x16_bf16 v[4:19], v[50:53], v[104:107], v[4:19]
	s_nop 8
	v_cndmask_b32_e32 v34, v191, v34, vcc
	v_cmp_le_u32_e32 vcc, v2, v0
	v_add_u32_e32 v2, 2, v204
	s_nop 0
	v_cndmask_b32_e32 v35, v191, v35, vcc
	v_cmp_le_u32_e32 vcc, v2, v0
	v_add_u32_e32 v2, 3, v204
	v_cndmask_b32_e64 v4, v4, v191, s[42:43]
	v_cndmask_b32_e32 v6, v191, v6, vcc
	v_cmp_le_u32_e32 vcc, v3, v0
	v_add_u32_e32 v3, 35, v204
	v_cndmask_b32_e64 v5, v191, v5, s[44:45]
	v_cndmask_b32_e32 v36, v191, v36, vcc
	v_cmp_le_u32_e32 vcc, v2, v0
	v_add_u32_e32 v2, 8, v204
	s_nop 0
	v_cndmask_b32_e32 v7, v191, v7, vcc
	v_cmp_le_u32_e32 vcc, v3, v0
	v_add_u32_e32 v3, 40, v204
	s_nop 0
	v_cndmask_b32_e32 v37, v191, v37, vcc
	v_cmp_le_u32_e32 vcc, v2, v0
	v_add_u32_e32 v2, 9, v204
	s_nop 0
	v_cndmask_b32_e32 v8, v191, v8, vcc
	v_cmp_le_u32_e32 vcc, v3, v0
	v_add_u32_e32 v3, 41, v204
	s_nop 0
	v_cndmask_b32_e32 v38, v191, v38, vcc
	v_cmp_le_u32_e32 vcc, v2, v0
	v_add_u32_e32 v2, 10, v204
	s_nop 0
	v_cndmask_b32_e32 v9, v191, v9, vcc
	v_cmp_le_u32_e32 vcc, v3, v0
	v_add_u32_e32 v3, 42, v204
	s_nop 0
	v_cndmask_b32_e32 v39, v191, v39, vcc
	v_cmp_le_u32_e32 vcc, v2, v0
	v_add_u32_e32 v2, 11, v204
	s_nop 0
	v_cndmask_b32_e32 v10, v191, v10, vcc
	v_cmp_le_u32_e32 vcc, v3, v0
	v_add_u32_e32 v3, 43, v204
	s_nop 0
	v_cndmask_b32_e32 v40, v191, v40, vcc
	v_cmp_le_u32_e32 vcc, v2, v0
	v_add_u32_e32 v2, 16, v204
	s_nop 0
	v_cndmask_b32_e32 v11, v191, v11, vcc
	v_cmp_le_u32_e32 vcc, v3, v0
	v_add_u32_e32 v3, 48, v204
	s_nop 0
	v_cndmask_b32_e32 v41, v191, v41, vcc
	v_cmp_le_u32_e32 vcc, v2, v0
	v_add_u32_e32 v2, 17, v204
	s_nop 0
	v_cndmask_b32_e32 v12, v191, v12, vcc
	v_cmp_le_u32_e32 vcc, v3, v0
	v_add_u32_e32 v3, 49, v204
	s_nop 0
	v_cndmask_b32_e32 v42, v191, v42, vcc
	v_cmp_le_u32_e32 vcc, v2, v0
	v_add_u32_e32 v2, 18, v204
	s_nop 0
	v_cndmask_b32_e32 v13, v191, v13, vcc
	v_cmp_le_u32_e32 vcc, v3, v0
	v_add_u32_e32 v3, 50, v204
	s_nop 0
	v_cndmask_b32_e32 v43, v191, v43, vcc
	v_cmp_le_u32_e32 vcc, v2, v0
	v_add_u32_e32 v2, 19, v204
	s_nop 0
	v_cndmask_b32_e32 v14, v191, v14, vcc
	v_cmp_le_u32_e32 vcc, v3, v0
; template <int MODE, bool WINDOW>
; __device__ __forceinline__ void attn_tile(const LAS unsigned char* buf, const bf16x8* qr, f32x16* o, float& m, float& l, int qpos, int kbase, int r32, int hi, const bool CAUSAL) {
;     ...
;         for (int r = 0; r < 16; ++r) {
;             const int kv0 = kbase + (r & 3) + 8 * (r >> 2) + 4 * hi, kv1 = kv0 + 32;
;             bool v0 = true, v1 = true;
;             if (CAUSAL) { v0 = kv0 <= qpos; v1 = kv1 <= qpos; }
;             if (WINDOW) { v0 = v0 && (qpos - kv0 < 128); v1 = v1 && (qpos - kv1 < 128); }
;             p0[r] = v0 ? p0[r] : -INFINITY; p1[r] = v1 ? p1[r] : -INFINITY;
;         }
;     }
;     asm volatile("s_nop 15\n\ts_nop 7" : "+v"(p0), "+v"(p1));
;     float mxa = max3f(p0[0], p1[0], p0[1]), mxb = max3f(p1[1], p0[2], p1[2]);
; #pragma unroll
;     for (int r = 3; r < 15; r += 2) { mxa = max3f(mxa, p0[r], p1[r]); mxb = max3f(mxb, p0[r + 1], p1[r + 1]); }
;     mxa = max3f(mxa, p0[15], p1[15]);
;     const float mx = xhalf_max(max2f(mxa, mxb));
;     bf16x8 va[4], vb[4];
; #pragma unroll
;     for (int g = 0; g < 4; ++g) {
;         const LAS unsigned char* vp = Vt + (32 * (g & 1) + r32) * VT_PITCH + (16 * (g >> 1) + 4 * hi) * 2;
;         const s16x4 lo = *(const LAS s16x4*)vp, h4 = *(const LAS s16x4*)(vp + 16), lo2 = *(const LAS s16x4*)(vp + 64), h42 = *(const LAS s16x4*)(vp + 80);
;         va[g] = (bf16x8){lo[0], lo[1], lo[2], lo[3], h4[0], h4[1], h4[2], h4[3]};
;         vb[g] = (bf16x8){lo2[0], lo2[1], lo2[2], lo2[3], h42[0], h42[1], h42[2], h42[3]};
;     }
;     const float mn = max2f(m, mx);
;     if (__any(mn > m)) {
;         const float alpha = __builtin_amdgcn_exp2f((m - mn) * LOG2E);
;         l *= alpha;
; #pragma unroll
;         for (int r = 0; r < 16; ++r) { o[0][r] *= alpha; o[1][r] *= alpha; }
;     }
;     m = mn;
;     const float nm2 = -mn * LOG2E;
;     float rs = 0.f;
; #pragma unroll
;     for (int r = 0; r < 16; ++r) { p0[r] = __builtin_amdgcn_exp2f(__builtin_fmaf(p0[r], LOG2E, nm2)); rs += p0[r]; }
;     v4u pw0, pw1;
;     pw0.x = cvtpk(p0[0], p0[1]); pw0.y = cvtpk(p0[2], p0[3]); pw0.z = cvtpk(p0[4], p0[5]); pw0.w = cvtpk(p0[6], p0[7]);
;     pw1.x = cvtpk(p0[8], p0[9]); pw1.y = cvtpk(p0[10], p0[11]); pw1.z = cvtpk(p0[12], p0[13]); pw1.w = cvtpk(p0[14], p0[15]);
;     __builtin_amdgcn_sched_barrier(0);
; #pragma unroll
;     for (int g = 0; g < 4; ++g) {
	v_add_u32_e32 v3, 51, v204
	s_nop 0
	v_cndmask_b32_e32 v44, v191, v44, vcc
	v_cmp_le_u32_e32 vcc, v2, v0
	v_add_u32_e32 v2, 24, v204
	s_nop 0
	v_cndmask_b32_e32 v15, v191, v15, vcc
	v_cmp_le_u32_e32 vcc, v3, v0
	v_add_u32_e32 v3, 56, v204
	s_nop 0
	v_cndmask_b32_e32 v45, v191, v45, vcc
	v_cmp_le_u32_e32 vcc, v2, v0
	v_add_u32_e32 v2, 25, v204
	s_nop 0
	v_cndmask_b32_e32 v16, v191, v16, vcc
	v_cmp_le_u32_e32 vcc, v3, v0
	v_add_u32_e32 v3, 57, v204
	s_nop 0
	v_cndmask_b32_e32 v46, v191, v46, vcc
	v_cmp_le_u32_e32 vcc, v2, v0
	v_add_u32_e32 v2, 26, v204
	s_nop 0
	v_cndmask_b32_e32 v17, v191, v17, vcc
	v_cmp_le_u32_e32 vcc, v3, v0
	v_add_u32_e32 v3, 58, v204
	s_nop 0
	v_cndmask_b32_e32 v47, v191, v47, vcc
	v_cmp_le_u32_e32 vcc, v2, v0
	v_add_u32_e32 v2, 27, v204
	s_nop 0
	v_cndmask_b32_e32 v18, v191, v18, vcc
	v_cmp_le_u32_e32 vcc, v3, v0
	v_add_u32_e32 v3, 59, v204
	s_nop 0
	v_cndmask_b32_e32 v48, v191, v48, vcc
	v_cmp_le_u32_e32 vcc, v2, v0
	s_nop 1
	v_cndmask_b32_e32 v19, v191, v19, vcc
	v_cmp_le_u32_e32 vcc, v3, v0
	s_nop 1
	v_cndmask_b32_e32 v49, v191, v49, vcc
	s_nop 11
	s_nop 0
	v_max3_f32 v2, v4, v34, v5
	v_max3_f32 v3, v35, v6, v36
	v_max3_f32 v2, v2, v7, v37
	v_max3_f32 v3, v3, v8, v38
	v_max3_f32 v2, v2, v9, v39
	v_max3_f32 v3, v3, v10, v40
	v_max3_f32 v2, v2, v11, v41
	v_max3_f32 v3, v3, v12, v42
	v_max3_f32 v2, v2, v13, v43
	v_max3_f32 v3, v3, v14, v44
	v_max3_f32 v2, v2, v15, v45
	v_max3_f32 v3, v3, v16, v46
	v_max3_f32 v2, v2, v17, v47
	v_max3_f32 v3, v3, v18, v48
	v_max3_f32 v2, v2, v19, v49
	v_max_f32_e32 v2, v2, v3
	v_mov_b32_e32 v3, v2
	s_nop 1
	v_permlane32_swap_b32_e32 v2, v3
	v_max_f32_e32 v2, v2, v3
	v_add3_u32 v3, s29, v201, v158
	v_max_f32_e32 v205, v203, v2
	v_add_u32_e32 v20, 0x2000, v3
	v_sub_f32_e32 v2, v203, v205
	v_mul_f32_e32 v2, 0x3fb8aa3b, v2
	v_exp_f32_e32 v2, v2
	v_cmp_gt_f32_e32 vcc, v205, v203
	v_add_u32_e32 v3, 0x3000, v3
	s_cmp_eq_u64 vcc, 0
	ds_read2_b64 v[58:61], v20 offset0:136 offset1:138
	ds_read2_b64 v[108:111], v3 offset0:160 offset1:162
	ds_read2_b64 v[62:65], v3 offset0:168 offset1:170
	ds_read2_b64 v[112:115], v20 offset0:128 offset1:130
	ds_read2_b64 v[116:119], v20 offset0:132 offset1:134
	ds_read2_b64 v[54:57], v20 offset0:140 offset1:142
	ds_read2_b64 v[120:123], v3 offset0:164 offset1:166
	ds_read2_b64 v[50:53], v3 offset0:172 offset1:174
	v_mul_f32_e32 v3, 0, v2
	s_cselect_b64 s[16:17], -1, 0
	v_mul_f32_e32 v67, 0xbfb8aa3b, v205
	v_cndmask_b32_e64 v66, v2, 1.0, s[16:17]
	v_cndmask_b32_e64 v2, v3, 0, s[16:17]
	v_fmamk_f32 v3, v4, 0x3fb8aa3b, v67
	v_exp_f32_e32 v3, v3
	v_fmamk_f32 v4, v5, 0x3fb8aa3b, v67
	v_exp_f32_e32 v4, v4
	v_fmamk_f32 v5, v6, 0x3fb8aa3b, v67
	v_exp_f32_e32 v5, v5
	v_fmamk_f32 v6, v7, 0x3fb8aa3b, v67
	v_exp_f32_e32 v6, v6
	v_fmamk_f32 v8, v8, 0x3fb8aa3b, v67
	v_add_f32_e32 v7, 0, v3
	v_exp_f32_e32 v8, v8
	v_fmamk_f32 v9, v9, 0x3fb8aa3b, v67
	v_add_f32_e32 v7, v4, v7
	v_exp_f32_e32 v9, v9
	v_fmamk_f32 v10, v10, 0x3fb8aa3b, v67
	v_add_f32_e32 v7, v5, v7
	v_exp_f32_e32 v10, v10
	v_fmamk_f32 v11, v11, 0x3fb8aa3b, v67
	v_add_f32_e32 v7, v6, v7
	v_exp_f32_e32 v11, v11
	v_fmamk_f32 v12, v12, 0x3fb8aa3b, v67
	v_add_f32_e32 v7, v8, v7
	v_exp_f32_e32 v12, v12
	v_fmamk_f32 v13, v13, 0x3fb8aa3b, v67
	v_add_f32_e32 v7, v9, v7
	v_exp_f32_e32 v13, v13
	v_fmamk_f32 v14, v14, 0x3fb8aa3b, v67
	v_add_f32_e32 v7, v10, v7
	v_exp_f32_e32 v14, v14
	v_fmamk_f32 v15, v15, 0x3fb8aa3b, v67
	v_add_f32_e32 v7, v11, v7
	v_exp_f32_e32 v15, v15
	v_fmamk_f32 v16, v16, 0x3fb8aa3b, v67
	v_add_f32_e32 v7, v12, v7
	v_exp_f32_e32 v16, v16
	v_fmamk_f32 v17, v17, 0x3fb8aa3b, v67
	v_add_f32_e32 v7, v13, v7
	v_exp_f32_e32 v17, v17
	v_fmamk_f32 v18, v18, 0x3fb8aa3b, v67
	v_add_f32_e32 v7, v14, v7
	v_exp_f32_e32 v18, v18
	v_fmamk_f32 v19, v19, 0x3fb8aa3b, v67
	v_add_f32_e32 v7, v15, v7
	v_exp_f32_e32 v19, v19
	v_add_f32_e32 v7, v16, v7
	v_add_f32_e32 v7, v17, v7
	v_add_f32_e32 v7, v18, v7
	v_add_f32_e32 v132, v19, v7
	v_cvt_pk_bf16_f32 v124, v3, v4
	v_cvt_pk_bf16_f32 v125, v5, v6
	v_cvt_pk_bf16_f32 v126, v8, v9
	v_cvt_pk_bf16_f32 v127, v10, v11
	v_cvt_pk_bf16_f32 v128, v12, v13
	v_cvt_pk_bf16_f32 v129, v14, v15
	v_cvt_pk_bf16_f32 v130, v16, v17
	v_cvt_pk_bf16_f32 v131, v18, v19
	v_mov_b32_e32 v3, v2
	v_mov_b32_e32 v4, v2
	v_mov_b32_e32 v5, v2
	v_mov_b32_e32 v6, v2
	v_mov_b32_e32 v7, v2
	v_mov_b32_e32 v8, v2
	v_mov_b32_e32 v9, v2
	v_mov_b32_e32 v10, v2
	v_mov_b32_e32 v11, v2
	v_mov_b32_e32 v12, v2
	v_mov_b32_e32 v13, v2
	v_mov_b32_e32 v14, v2
	v_mov_b32_e32 v15, v2
	v_mov_b32_e32 v16, v2
	v_mov_b32_e32 v17, v2
	v_fmamk_f32 v34, v34, 0x3fb8aa3b, v67
	v_exp_f32_e32 v34, v34
	s_waitcnt lgkmcnt(4)
	v_mfma_f32_32x32x16_bf16 v[18:33], v[112:115], v[124:127], v[2:17]
	v_fmamk_f32 v35, v35, 0x3fb8aa3b, v67
	v_exp_f32_e32 v35, v35
	v_fmamk_f32 v36, v36, 0x3fb8aa3b, v67
	v_exp_f32_e32 v36, v36
	v_fmamk_f32 v37, v37, 0x3fb8aa3b, v67
	v_exp_f32_e32 v37, v37
	v_add_f32_e32 v112, v34, v132
	v_add_f32_e32 v112, v35, v112
	v_add_f32_e32 v112, v36, v112
	v_add_f32_e32 v112, v37, v112
	v_mfma_f32_32x32x16_bf16 v[2:17], v[108:111], v[124:127], v[2:17]
	v_fmamk_f32 v38, v38, 0x3fb8aa3b, v67
	v_exp_f32_e32 v38, v38
	v_fmamk_f32 v39, v39, 0x3fb8aa3b, v67
	v_exp_f32_e32 v39, v39
	v_fmamk_f32 v40, v40, 0x3fb8aa3b, v67
	v_exp_f32_e32 v40, v40
	v_fmamk_f32 v41, v41, 0x3fb8aa3b, v67
	v_exp_f32_e32 v41, v41
	v_add_f32_e32 v108, v38, v112
	v_add_f32_e32 v108, v39, v108
	v_add_f32_e32 v108, v40, v108
	v_add_f32_e32 v108, v41, v108
	s_waitcnt lgkmcnt(3)
	v_mfma_f32_32x32x16_bf16 v[18:33], v[116:119], v[128:131], v[18:33]
	v_fmamk_f32 v42, v42, 0x3fb8aa3b, v67
	v_exp_f32_e32 v42, v42
	v_fmamk_f32 v43, v43, 0x3fb8aa3b, v67
	v_exp_f32_e32 v43, v43
	v_fmamk_f32 v44, v44, 0x3fb8aa3b, v67
	v_exp_f32_e32 v44, v44
	v_fmamk_f32 v45, v45, 0x3fb8aa3b, v67
	v_exp_f32_e32 v45, v45
	v_add_f32_e32 v108, v42, v108
	v_add_f32_e32 v108, v43, v108
	v_add_f32_e32 v108, v44, v108
	v_add_f32_e32 v108, v45, v108
	v_fmamk_f32 v46, v46, 0x3fb8aa3b, v67
	s_waitcnt lgkmcnt(1)
	v_mfma_f32_32x32x16_bf16 v[2:17], v[120:123], v[128:131], v[2:17]
	v_exp_f32_e32 v46, v46
	v_fmamk_f32 v47, v47, 0x3fb8aa3b, v67
	v_exp_f32_e32 v47, v47
	v_fmamk_f32 v48, v48, 0x3fb8aa3b, v67
	v_exp_f32_e32 v48, v48
	v_fmac_f32_e32 v67, 0x3fb8aa3b, v49
	v_exp_f32_e32 v49, v67
	v_add_f32_e32 v108, v46, v108
	v_add_f32_e32 v108, v47, v108
	v_add_f32_e32 v108, v48, v108
	v_add_f32_e32 v167, v49, v108
	v_cvt_pk_bf16_f32 v34, v34, v35
	v_cvt_pk_bf16_f32 v35, v36, v37
	v_cvt_pk_bf16_f32 v36, v38, v39
	v_cvt_pk_bf16_f32 v37, v40, v41
	v_fmac_f32_e32 v167, v178, v66
	s_cmp_lt_i32 s28, 1
	v_mfma_f32_32x32x16_bf16 v[18:33], v[58:61], v[34:37], v[18:33]
	v_mfma_f32_32x32x16_bf16 v[2:17], v[62:65], v[34:37], v[2:17]
	v_cvt_pk_bf16_f32 v34, v42, v43
	v_cvt_pk_bf16_f32 v35, v44, v45
	v_cvt_pk_bf16_f32 v36, v46, v47
	v_cvt_pk_bf16_f32 v37, v48, v49
	s_nop 1
	v_mfma_f32_32x32x16_bf16 v[18:33], v[54:57], v[34:37], v[18:33]
	s_waitcnt lgkmcnt(0)
	v_mfma_f32_32x32x16_bf16 v[2:17], v[50:53], v[34:37], v[2:17]
	s_cbranch_scc1 .LBB0_277
; #define LAS __attribute__((address_space(3)))
; template <int MODE, bool WINDOW>
; __device__ __forceinline__ void attn_tile(const LAS unsigned char* buf, const bf16x8* qr, f32x16* o, float& m, float& l, int qpos, int kbase, int r32, int hi, const bool CAUSAL) {
;     ...
;     for (int d0 = 0; d0 < 4; ++d0) {
;         const bf16x8 a0 = *(const LAS bf16x8*)(Ks + r32 * KS_PITCH + d0 * 32 + hi * 16);
;         const bf16x8 a1 = *(const LAS bf16x8*)(Ks + (32 + r32) * KS_PITCH + d0 * 32 + hi * 16);
;         p0 = __builtin_amdgcn_mfma_f32_32x32x16_bf16(a0, qr[d0], p0, 0, 0, 0);
;         p1 = __builtin_amdgcn_mfma_f32_32x32x16_bf16(a1, qr[d0], p1, 0, 0, 0);
;     }
;     if (CAUSAL || WINDOW) {
; #pragma unroll
;         for (int r = 0; r < 16; ++r) {
;             const int kv0 = kbase + (r & 3) + 8 * (r >> 2) + 4 * hi, kv1 = kv0 + 32;
;             bool v0 = true, v1 = true;
;             if (CAUSAL) { v0 = kv0 <= qpos; v1 = kv1 <= qpos; }
;             if (WINDOW) { v0 = v0 && (qpos - kv0 < 128); v1 = v1 && (qpos - kv1 < 128); }
;             p0[r] = v0 ? p0[r] : -INFINITY; p1[r] = v1 ? p1[r] : -INFINITY;
;         }
;     }
;     asm volatile("s_nop 15\n\ts_nop 7" : "+v"(p0), "+v"(p1));
;     float mxa = max3f(p0[0], p1[0], p0[1]), mxb = max3f(p1[1], p0[2], p1[2]);
; #pragma unroll
;     for (int r = 3; r < 15; r += 2) { mxa = max3f(mxa, p0[r], p1[r]); mxb = max3f(mxb, p0[r + 1], p1[r + 1]); }
;     mxa = max3f(mxa, p0[15], p1[15]);
;     const float mx = xhalf_max(max2f(mxa, mxb));
;     bf16x8 va[4], vb[4];
; #pragma unroll
;     for (int g = 0; g < 4; ++g) {
;         const LAS unsigned char* vp = Vt + (32 * (g & 1) + r32) * VT_PITCH + (16 * (g >> 1) + 4 * hi) * 2;
;         const s16x4 lo = *(const LAS s16x4*)vp, h4 = *(const LAS s16x4*)(vp + 16), lo2 = *(const LAS s16x4*)(vp + 64), h42 = *(const LAS s16x4*)(vp + 80);
;         va[g] = (bf16x8){lo[0], lo[1], lo[2], lo[3], h4[0], h4[1], h4[2], h4[3]};
;         vb[g] = (bf16x8){lo2[0], lo2[1], lo2[2], lo2[3], h42[0], h42[1], h42[2], h42[3]};
;     }
;     const float mn = max2f(m, mx);
;     if (__any(mn > m)) {
;         const float alpha = __builtin_amdgcn_exp2f((m - mn) * LOG2E);
;         l *= alpha;
; #pragma unroll
;         for (int r = 0; r < 16; ++r) { o[0][r] *= alpha; o[1][r] *= alpha; }
;     }
	s_add_i32 s16, s19, 5
	s_and_b32 s16, s16, 3
	s_mulk_i32 s16, 0x4800
	s_add_i32 s16, s16, 0
	v_add3_u32 v66, s16, v179, v199
	ds_read_b128 v[34:37], v66
	ds_read_b128 v[108:111], v66 offset:32
	s_waitcnt lgkmcnt(1)
	v_mfma_f32_32x32x16_bf16 v[50:65], v[34:37], v[92:95], 0
	ds_read_b128 v[34:37], v66 offset:4608
	ds_read_b128 v[112:115], v66 offset:4640
	s_waitcnt lgkmcnt(1)
	v_mfma_f32_32x32x16_bf16 v[34:49], v[34:37], v[92:95], 0
	v_mfma_f32_32x32x16_bf16 v[50:65], v[108:111], v[96:99], v[50:65]
	s_waitcnt lgkmcnt(0)
	v_mfma_f32_32x32x16_bf16 v[34:49], v[112:115], v[96:99], v[34:49]
	ds_read_b128 v[108:111], v66 offset:64
	ds_read_b128 v[112:115], v66 offset:96
	s_waitcnt lgkmcnt(1)
	v_mfma_f32_32x32x16_bf16 v[50:65], v[108:111], v[100:103], v[50:65]
	ds_read_b128 v[108:111], v66 offset:4672
	ds_read_b128 v[116:119], v66 offset:4704
	s_waitcnt lgkmcnt(1)
	v_mfma_f32_32x32x16_bf16 v[34:49], v[108:111], v[100:103], v[34:49]
	v_mfma_f32_32x32x16_bf16 v[50:65], v[112:115], v[104:107], v[50:65]
	s_waitcnt lgkmcnt(0)
	v_mfma_f32_32x32x16_bf16 v[34:49], v[116:119], v[104:107], v[34:49]
	s_nop 11
	s_nop 0
	v_max3_f32 v66, v50, v34, v51
	v_max3_f32 v67, v35, v52, v36
	v_max3_f32 v66, v66, v53, v37
	v_max3_f32 v67, v67, v54, v38
	v_max3_f32 v66, v66, v55, v39
	v_max3_f32 v67, v67, v56, v40
	v_max3_f32 v66, v66, v57, v41
	v_max3_f32 v67, v67, v58, v42
	v_max3_f32 v66, v66, v59, v43
	v_max3_f32 v67, v67, v60, v44
	v_max3_f32 v66, v66, v61, v45
	v_max3_f32 v67, v67, v62, v46
	v_max3_f32 v66, v66, v63, v47
	v_max3_f32 v67, v67, v64, v48
	v_max3_f32 v66, v66, v65, v49
	v_max_f32_e32 v66, v66, v67
	v_mov_b32_e32 v67, v66
	s_nop 1
	v_permlane32_swap_b32_e32 v66, v67
	v_max_f32_e32 v66, v66, v67
	v_add3_u32 v67, s16, v201, v158
	v_add_u32_e32 v108, 0x2000, v67
	v_add_u32_e32 v67, 0x3000, v67
	ds_read2_b64 v[136:139], v108 offset0:128 offset1:130
	ds_read2_b64 v[128:131], v108 offset0:132 offset1:134
	ds_read2_b64 v[116:119], v108 offset0:136 offset1:138
	ds_read2_b64 v[132:135], v67 offset0:160 offset1:162
	ds_read2_b64 v[120:123], v67 offset0:168 offset1:170
	ds_read2_b64 v[112:115], v108 offset0:140 offset1:142
	ds_read2_b64 v[124:127], v67 offset0:164 offset1:166
	ds_read2_b64 v[108:111], v67 offset0:172 offset1:174
	v_max_f32_e32 v66, v205, v66
	s_nop 0
	v_cmp_gt_f32_e32 vcc, v66, v205
	s_cbranch_vccz .LBB0_276
	v_sub_f32_e32 v67, v205, v66
	v_mul_f32_e32 v67, 0x3fb8aa3b, v67
	v_exp_f32_e32 v206, v67
	s_nop 0
	v_mul_f32_e32 v167, v167, v206
	v_pk_mul_f32 v[16:17], v[16:17], v[206:207] op_sel_hi:[1,0]
	v_pk_mul_f32 v[14:15], v[14:15], v[206:207] op_sel_hi:[1,0]
	v_pk_mul_f32 v[12:13], v[12:13], v[206:207] op_sel_hi:[1,0]
	v_pk_mul_f32 v[10:11], v[10:11], v[206:207] op_sel_hi:[1,0]
	v_pk_mul_f32 v[8:9], v[8:9], v[206:207] op_sel_hi:[1,0]
	v_pk_mul_f32 v[6:7], v[6:7], v[206:207] op_sel_hi:[1,0]
	v_pk_mul_f32 v[4:5], v[4:5], v[206:207] op_sel_hi:[1,0]
	v_pk_mul_f32 v[2:3], v[2:3], v[206:207] op_sel_hi:[1,0]
	v_pk_mul_f32 v[32:33], v[32:33], v[206:207] op_sel_hi:[1,0]
	v_pk_mul_f32 v[30:31], v[30:31], v[206:207] op_sel_hi:[1,0]
	v_pk_mul_f32 v[28:29], v[28:29], v[206:207] op_sel_hi:[1,0]
	v_pk_mul_f32 v[26:27], v[26:27], v[206:207] op_sel_hi:[1,0]
	v_pk_mul_f32 v[24:25], v[24:25], v[206:207] op_sel_hi:[1,0]
	v_pk_mul_f32 v[22:23], v[22:23], v[206:207] op_sel_hi:[1,0]
	v_pk_mul_f32 v[20:21], v[20:21], v[206:207] op_sel_hi:[1,0]
	v_pk_mul_f32 v[18:19], v[18:19], v[206:207] op_sel_hi:[1,0]

; #define LAS __attribute__((address_space(3)))
; __device__ __forceinline__ float max3f(float a, float b, float c) { float r; asm("v_max3_f32 %0, %1, %2, %3" : "=v"(r) : "v"(a), "v"(b), "v"(c)); return r; }
; __device__ __forceinline__ float max2f(float a, float b) { float r; asm("v_max_f32_e32 %0, %1, %2" : "=v"(r) : "v"(a), "v"(b)); return r; }
; template <int MODE, bool WINDOW>
; __device__ __forceinline__ void attn_tile(const LAS unsigned char* buf, const bf16x8* qr, f32x16* o, float& m, float& l, int qpos, int kbase, int r32, int hi, const bool CAUSAL) {
;     ...
;     for (int d0 = 0; d0 < 4; ++d0) {
;         const bf16x8 a0 = *(const LAS bf16x8*)(Ks + r32 * KS_PITCH + d0 * 32 + hi * 16);
;         const bf16x8 a1 = *(const LAS bf16x8*)(Ks + (32 + r32) * KS_PITCH + d0 * 32 + hi * 16);
;         p0 = __builtin_amdgcn_mfma_f32_32x32x16_bf16(a0, qr[d0], p0, 0, 0, 0);
;         p1 = __builtin_amdgcn_mfma_f32_32x32x16_bf16(a1, qr[d0], p1, 0, 0, 0);
;     }
;     if (CAUSAL || WINDOW) {
; #pragma unroll
;         for (int r = 0; r < 16; ++r) {
;             const int kv0 = kbase + (r & 3) + 8 * (r >> 2) + 4 * hi, kv1 = kv0 + 32;
;             bool v0 = true, v1 = true;
;             if (CAUSAL) { v0 = kv0 <= qpos; v1 = kv1 <= qpos; }
;             if (WINDOW) { v0 = v0 && (qpos - kv0 < 128); v1 = v1 && (qpos - kv1 < 128); }
;             p0[r] = v0 ? p0[r] : -INFINITY; p1[r] = v1 ? p1[r] : -INFINITY;
;         }
;     }
;     asm volatile("s_nop 15\n\ts_nop 7" : "+v"(p0), "+v"(p1));
;     float mxa = max3f(p0[0], p1[0], p0[1]), mxb = max3f(p1[1], p0[2], p1[2]);
; #pragma unroll
;     for (int r = 3; r < 15; r += 2) { mxa = max3f(mxa, p0[r], p1[r]); mxb = max3f(mxb, p0[r + 1], p1[r + 1]); }
;     mxa = max3f(mxa, p0[15], p1[15]);
;     const float mx = xhalf_max(max2f(mxa, mxb));
;     bf16x8 va[4], vb[4];
; #pragma unroll
;     for (int g = 0; g < 4; ++g) {
;         const LAS unsigned char* vp = Vt + (32 * (g & 1) + r32) * VT_PITCH + (16 * (g >> 1) + 4 * hi) * 2;
;         const s16x4 lo = *(const LAS s16x4*)vp, h4 = *(const LAS s16x4*)(vp + 16), lo2 = *(const LAS s16x4*)(vp + 64), h42 = *(const LAS s16x4*)(vp + 80);
;         va[g] = (bf16x8){lo[0], lo[1], lo[2], lo[3], h4[0], h4[1], h4[2], h4[3]};
;         vb[g] = (bf16x8){lo2[0], lo2[1], lo2[2], lo2[3], h42[0], h42[1], h42[2], h42[3]};
;     }
;     const float mn = max2f(m, mx);
;     if (__any(mn > m)) {
.LBB0_277:
	s_cmp_lt_i32 s28, 2
	s_cbranch_scc1 .LBB0_262
	s_and_b32 s16, s19, 3
	s_mulk_i32 s16, 0x4800
	s_add_i32 s16, s16, 0
	v_add3_u32 v116, s16, v179, v199
	ds_read_b128 v[34:37], v116
	ds_read_b128 v[108:111], v116 offset:32
	ds_read_b128 v[50:53], v116 offset:4608
	ds_read_b128 v[112:115], v116 offset:4640
	s_movk_i32 s17, 0xff7f
	s_waitcnt lgkmcnt(3)
	v_mfma_f32_32x32x16_bf16 v[34:49], v[34:37], v[92:95], 0
	s_waitcnt lgkmcnt(1)
	v_mfma_f32_32x32x16_bf16 v[52:67], v[50:53], v[92:95], 0
	v_add_u32_e32 v51, 0xffffff80, v204
	v_mfma_f32_32x32x16_bf16 v[34:49], v[108:111], v[96:99], v[34:49]
	s_waitcnt lgkmcnt(0)
	v_mfma_f32_32x32x16_bf16 v[52:67], v[112:115], v[96:99], v[52:67]
	ds_read_b128 v[92:95], v116 offset:64
	ds_read_b128 v[96:99], v116 offset:96
	s_waitcnt lgkmcnt(1)
	v_mfma_f32_32x32x16_bf16 v[34:49], v[92:95], v[100:103], v[34:49]
	ds_read_b128 v[92:95], v116 offset:4672
	ds_read_b128 v[108:111], v116 offset:4704
	s_waitcnt lgkmcnt(1)
	v_mfma_f32_32x32x16_bf16 v[52:67], v[92:95], v[100:103], v[52:67]
	v_add_u32_e32 v92, 0xffffff80, v0
	v_subrev_u32_e32 v93, 32, v0
	v_sub_u32_e32 v94, v93, v51
	v_cmp_gt_i32_e32 vcc, v51, v92
	v_mfma_f32_32x32x16_bf16 v[34:49], v[96:99], v[104:107], v[34:49]
	s_waitcnt lgkmcnt(0)
	v_mfma_f32_32x32x16_bf16 v[52:67], v[108:111], v[104:107], v[52:67]
	s_nop 9
	v_cndmask_b32_e32 v50, v191, v34, vcc
	v_cmp_gt_i32_e32 vcc, s30, v94
	s_nop 1
	v_cndmask_b32_e32 v34, v191, v52, vcc
	v_sub_u32_e32 v52, v51, v93
	v_cmp_ge_i32_e32 vcc, v51, v92
	s_nop 1
	v_cndmask_b32_e32 v51, v191, v35, vcc
	v_cmp_lt_i32_e32 vcc, s17, v52
	v_add_u32_e32 v52, 0xffffff82, v204
	s_nop 0
	v_cndmask_b32_e32 v35, v191, v53, vcc
	v_sub_u32_e32 v53, v93, v52
	v_cmp_gt_i32_e32 vcc, v52, v92
	s_nop 1
	v_cndmask_b32_e32 v52, v191, v36, vcc
	v_cmp_gt_i32_e32 vcc, s30, v53
	v_add_u32_e32 v53, 0xffffff83, v204
	s_nop 0
	v_cndmask_b32_e32 v36, v191, v54, vcc
	v_sub_u32_e32 v54, v93, v53
	v_cmp_gt_i32_e32 vcc, v53, v92
	s_nop 1
	v_cndmask_b32_e32 v53, v191, v37, vcc
	v_cmp_gt_i32_e32 vcc, s30, v54
	v_add_u32_e32 v54, 0xffffff88, v204
	s_nop 0
	v_cndmask_b32_e32 v37, v191, v55, vcc
	v_sub_u32_e32 v55, v93, v54
	v_cmp_gt_i32_e32 vcc, v54, v92
	s_nop 1
	v_cndmask_b32_e32 v54, v191, v38, vcc
	v_cmp_gt_i32_e32 vcc, s30, v55
	v_add_u32_e32 v55, 0xffffff89, v204
	s_nop 0
	v_cndmask_b32_e32 v38, v191, v56, vcc
	v_sub_u32_e32 v56, v93, v55
	v_cmp_gt_i32_e32 vcc, v55, v92
	s_nop 1
	v_cndmask_b32_e32 v55, v191, v39, vcc
	v_cmp_gt_i32_e32 vcc, s30, v56
	v_add_u32_e32 v56, 0xffffff8a, v204
	s_nop 0
	v_cndmask_b32_e32 v39, v191, v57, vcc
	v_sub_u32_e32 v57, v93, v56
	v_cmp_gt_i32_e32 vcc, v56, v92
	s_nop 1
	v_cndmask_b32_e32 v56, v191, v40, vcc
	v_cmp_gt_i32_e32 vcc, s30, v57
	v_add_u32_e32 v57, 0xffffff8b, v204
	s_nop 0
	v_cndmask_b32_e32 v40, v191, v58, vcc
	v_sub_u32_e32 v58, v93, v57
	v_cmp_gt_i32_e32 vcc, v57, v92
	s_nop 1
	v_cndmask_b32_e32 v57, v191, v41, vcc
	v_cmp_gt_i32_e32 vcc, s30, v58
	v_add_u32_e32 v58, 0xffffff90, v204
	s_nop 0
	v_cndmask_b32_e32 v41, v191, v59, vcc
	v_sub_u32_e32 v59, v93, v58
	v_cmp_gt_i32_e32 vcc, v58, v92
	s_nop 1
	v_cndmask_b32_e32 v58, v191, v42, vcc
	v_cmp_gt_i32_e32 vcc, s30, v59
	v_add_u32_e32 v59, 0xffffff91, v204
	s_nop 0
	v_cndmask_b32_e32 v42, v191, v60, vcc
	v_sub_u32_e32 v60, v93, v59
	v_cmp_gt_i32_e32 vcc, v59, v92
	s_nop 1
	v_cndmask_b32_e32 v59, v191, v43, vcc
	v_cmp_gt_i32_e32 vcc, s30, v60
	v_add_u32_e32 v60, 0xffffff92, v204
	s_nop 0
	v_cndmask_b32_e32 v43, v191, v61, vcc
	v_sub_u32_e32 v61, v93, v60
	v_cmp_gt_i32_e32 vcc, v60, v92
	s_nop 1
	v_cndmask_b32_e32 v60, v191, v44, vcc
	v_cmp_gt_i32_e32 vcc, s30, v61
	v_add_u32_e32 v61, 0xffffff93, v204
	s_nop 0
	v_cndmask_b32_e32 v44, v191, v62, vcc
	v_sub_u32_e32 v62, v93, v61
	v_cmp_gt_i32_e32 vcc, v61, v92
	s_nop 1
	v_cndmask_b32_e32 v61, v191, v45, vcc
	v_cmp_gt_i32_e32 vcc, s30, v62
	v_add_u32_e32 v62, 0xffffff98, v204
	s_nop 0
	v_cndmask_b32_e32 v45, v191, v63, vcc
	v_sub_u32_e32 v63, v93, v62
	v_cmp_gt_i32_e32 vcc, v62, v92
	s_nop 1
	v_cndmask_b32_e32 v62, v191, v46, vcc
	v_cmp_gt_i32_e32 vcc, s30, v63
	v_add_u32_e32 v63, 0xffffff99, v204
	s_nop 0
	v_cndmask_b32_e32 v46, v191, v64, vcc
	v_sub_u32_e32 v64, v93, v63
	v_cmp_gt_i32_e32 vcc, v63, v92
	s_nop 1
	v_cndmask_b32_e32 v63, v191, v47, vcc
	v_cmp_gt_i32_e32 vcc, s30, v64
	v_add_u32_e32 v64, 0xffffff9a, v204
	s_nop 0
	v_cndmask_b32_e32 v47, v191, v65, vcc
	v_sub_u32_e32 v65, v93, v64
	v_cmp_gt_i32_e32 vcc, v64, v92
	s_nop 1
	v_cndmask_b32_e32 v64, v191, v48, vcc
	v_cmp_gt_i32_e32 vcc, s30, v65
	v_add_u32_e32 v65, 0xffffff9b, v204
	s_nop 0
	v_cndmask_b32_e32 v48, v191, v66, vcc
	v_sub_u32_e32 v66, v93, v65
	v_cmp_gt_i32_e32 vcc, v65, v92
	s_nop 1
	v_cndmask_b32_e32 v65, v191, v49, vcc
	v_cmp_gt_i32_e32 vcc, s30, v66
	s_nop 1
	v_cndmask_b32_e32 v49, v191, v67, vcc
	s_nop 11
	s_nop 0
	v_max3_f32 v66, v50, v34, v51
	v_max3_f32 v67, v35, v52, v36
	v_max3_f32 v66, v66, v53, v37
	v_max3_f32 v67, v67, v54, v38
	v_max3_f32 v66, v66, v55, v39
	v_max3_f32 v67, v67, v56, v40
	v_max3_f32 v66, v66, v57, v41
	v_max3_f32 v67, v67, v58, v42
	v_max3_f32 v66, v66, v59, v43
	v_max3_f32 v67, v67, v60, v44
	v_max3_f32 v66, v66, v61, v45
	v_max3_f32 v67, v67, v62, v46
	v_max3_f32 v66, v66, v63, v47
	v_max3_f32 v67, v67, v64, v48
	v_max3_f32 v66, v66, v65, v49
	v_max_f32_e32 v66, v66, v67
	v_mov_b32_e32 v67, v66
	s_nop 1
	v_permlane32_swap_b32_e32 v66, v67
	v_max_f32_e32 v66, v66, v67
	v_add3_u32 v67, s16, v201, v158
	v_add_u32_e32 v92, 0x2000, v67
	v_add_u32_e32 v67, 0x3000, v67
	ds_read2_b64 v[120:123], v92 offset0:128 offset1:130
	ds_read2_b64 v[112:115], v92 offset0:132 offset1:134
	ds_read2_b64 v[100:103], v92 offset0:136 offset1:138
	ds_read2_b64 v[116:119], v67 offset0:160 offset1:162
	ds_read2_b64 v[104:107], v67 offset0:168 offset1:170
	ds_read2_b64 v[96:99], v92 offset0:140 offset1:142
	ds_read2_b64 v[108:111], v67 offset0:164 offset1:166
	ds_read2_b64 v[92:95], v67 offset0:172 offset1:174
	v_max_f32_e32 v66, v205, v66
	s_nop 0
	v_cmp_gt_f32_e32 vcc, v66, v205
	s_cbranch_vccz .LBB0_261
; template <int MODE, bool WINDOW>
; __device__ __forceinline__ void attn_tile(const LAS unsigned char* buf, const bf16x8* qr, f32x16* o, float& m, float& l, int qpos, int kbase, int r32, int hi, const bool CAUSAL) {
;     ...
;     if (__any(mn > m)) {
;         const float alpha = __builtin_amdgcn_exp2f((m - mn) * LOG2E);
;         l *= alpha;
; #pragma unroll
;         for (int r = 0; r < 16; ++r) { o[0][r] *= alpha; o[1][r] *= alpha; }
;     }
	v_sub_f32_e32 v67, v205, v66
	v_mul_f32_e32 v67, 0x3fb8aa3b, v67
	v_exp_f32_e32 v124, v67
	s_nop 0
	v_mul_f32_e32 v167, v167, v124
	v_pk_mul_f32 v[16:17], v[16:17], v[124:125] op_sel_hi:[1,0]
	v_pk_mul_f32 v[14:15], v[14:15], v[124:125] op_sel_hi:[1,0]
	v_pk_mul_f32 v[12:13], v[12:13], v[124:125] op_sel_hi:[1,0]
	v_pk_mul_f32 v[10:11], v[10:11], v[124:125] op_sel_hi:[1,0]
	v_pk_mul_f32 v[8:9], v[8:9], v[124:125] op_sel_hi:[1,0]
	v_pk_mul_f32 v[6:7], v[6:7], v[124:125] op_sel_hi:[1,0]
	v_pk_mul_f32 v[4:5], v[4:5], v[124:125] op_sel_hi:[1,0]
	v_pk_mul_f32 v[2:3], v[2:3], v[124:125] op_sel_hi:[1,0]
	v_pk_mul_f32 v[32:33], v[32:33], v[124:125] op_sel_hi:[1,0]
	v_pk_mul_f32 v[30:31], v[30:31], v[124:125] op_sel_hi:[1,0]
	v_pk_mul_f32 v[28:29], v[28:29], v[124:125] op_sel_hi:[1,0]
	v_pk_mul_f32 v[26:27], v[26:27], v[124:125] op_sel_hi:[1,0]
	v_pk_mul_f32 v[24:25], v[24:25], v[124:125] op_sel_hi:[1,0]
	v_pk_mul_f32 v[22:23], v[22:23], v[124:125] op_sel_hi:[1,0]
	v_pk_mul_f32 v[20:21], v[20:21], v[124:125] op_sel_hi:[1,0]
	v_pk_mul_f32 v[18:19], v[18:19], v[124:125] op_sel_hi:[1,0]
	s_branch .LBB0_261
